# attnA: wave priority raised from the start of a step's QK block until its barrier arrival, dropped for the post-arrival MFMAs
# speedup vs baseline: 1.0141x; 1.0141x over previous
.LBB0_1369:
	s_or_b32 s82, s34, 1
	s_lshl_b64 s[4:5], s[82:83], 7
	s_add_u32 s4, s8, s4
	s_addc_u32 s5, s9, s5
	s_add_u32 m0, s38, 0x8000
	s_nop 0
	global_load_lds_dwordx4 v198, s[4:5]
	s_add_u32 m0, s38, 0x9000
	s_nop 0
	global_load_lds_dwordx4 v199, s[4:5]
	s_add_u32 m0, s38, 0xa000
	s_nop 0
	global_load_lds_dwordx4 v200, s[4:5]
	s_add_u32 m0, s38, 0xb000
	s_nop 0
	global_load_lds_dwordx4 v201, s[4:5]
	v_cmp_lt_i32_e64 s[4:5], s34, v226
	s_and_saveexec_b64 s[22:23], s[4:5]
	s_cbranch_execz .LBB0_1371
	s_setprio 1
	ds_read_b128 v[2:5], v222 offset:24576
	ds_read_b128 v[6:9], v222 offset:28672
	ds_read_b128 v[10:13], v223 offset:24576
	ds_read_b128 v[244:247], v223 offset:28672
	s_waitcnt lgkmcnt(3)
	v_mfma_f32_32x32x16_bf16 v[128:143], v[2:5], v[160:163], v[16:31]
	v_exp_f32_e32 v32, v32
	v_exp_f32_e32 v33, v33
	ds_read_b128 v[2:5], v224 offset:24576
	s_waitcnt lgkmcnt(3)
	v_mfma_f32_32x32x16_bf16 v[144:159], v[6:9], v[160:163], v[16:31]
	v_exp_f32_e32 v34, v34
	v_exp_f32_e32 v35, v35
	ds_read_b128 v[6:9], v224 offset:28672
	s_waitcnt lgkmcnt(3)
	v_mfma_f32_32x32x16_bf16 v[128:143], v[10:13], v[164:167], v[128:143]
	v_exp_f32_e32 v36, v36
	v_exp_f32_e32 v37, v37
	v_add_f32_e32 v0, 0, v32
	ds_read_b128 v[10:13], v225 offset:24576
	s_waitcnt lgkmcnt(3)
	v_mfma_f32_32x32x16_bf16 v[144:159], v[244:247], v[164:167], v[144:159]
	v_exp_f32_e32 v38, v38
	v_exp_f32_e32 v39, v39
	v_add_f32_e32 v0, v33, v0
	ds_read_b128 v[244:247], v225 offset:28672
	s_waitcnt lgkmcnt(3)
	v_mfma_f32_32x32x16_bf16 v[128:143], v[2:5], v[168:171], v[128:143]
	v_cvt_pk_bf16_f32 v208, v32, v33
	v_add_f32_e32 v0, v34, v0
	v_add_f32_e32 v0, v35, v0
	s_waitcnt lgkmcnt(2)
	v_mfma_f32_32x32x16_bf16 v[144:159], v[6:9], v[168:171], v[144:159]
	v_cvt_pk_bf16_f32 v209, v34, v35
	v_add_f32_e32 v0, v36, v0
	v_add_f32_e32 v0, v37, v0
	s_waitcnt lgkmcnt(1)
	v_mfma_f32_32x32x16_bf16 v[128:143], v[10:13], v[172:175], v[128:143]
	v_cvt_pk_bf16_f32 v210, v36, v37
	v_add_f32_e32 v0, v38, v0
	s_waitcnt lgkmcnt(0)
	v_mfma_f32_32x32x16_bf16 v[144:159], v[244:247], v[172:175], v[144:159]
	v_cvt_pk_bf16_f32 v211, v38, v39
	v_add_f32_e32 v0, v39, v0
	s_or_b64 exec, exec, s[22:23]
	v_cmp_le_i32_e32 vcc, s34, v226
	s_and_saveexec_b64 s[22:23], vcc
	ds_read_b64 v[6:7], v228 offset:8192
	ds_read_b64 v[8:9], v229 offset:8192
	ds_read_b64 v[10:11], v230 offset:20480
	ds_read_b64 v[12:13], v231 offset:20480
	ds_read_b64 v[244:245], v230 offset:12288
	ds_read_b64 v[246:247], v231 offset:12288
	ds_read_b64 v[32:33], v230 offset:16384
	ds_read_b64 v[34:35], v231 offset:16384
	ds_read_b64 v[36:37], v232 offset:8192
	ds_read_b64 v[38:39], v233 offset:8192
	s_waitcnt lgkmcnt(8)
	v_mfma_f32_32x32x16_bf16 v[112:127], v[6:9], v[208:211], v[112:127]
	ds_read_b64 v[6:7], v234 offset:20480
	ds_read_b64 v[8:9], v235 offset:20480
	v_exp_f32_e32 v40, v40
	v_exp_f32_e32 v41, v41
	s_waitcnt lgkmcnt(8)
	v_mfma_f32_32x32x16_bf16 v[64:79], v[10:13], v[208:211], v[64:79]
	ds_read_b64 v[10:11], v234 offset:12288
	ds_read_b64 v[12:13], v235 offset:12288
	v_exp_f32_e32 v42, v42
	v_exp_f32_e32 v43, v43
	v_add_f32_e32 v0, v40, v0
	v_add_f32_e32 v0, v41, v0
	s_waitcnt lgkmcnt(8)
	v_mfma_f32_32x32x16_bf16 v[96:111], v[244:247], v[208:211], v[96:111]
	ds_read_b64 v[244:245], v234 offset:16384
	ds_read_b64 v[246:247], v235 offset:16384
	v_exp_f32_e32 v44, v44
	v_exp_f32_e32 v45, v45
	v_add_f32_e32 v0, v42, v0
	v_add_f32_e32 v0, v43, v0
	s_waitcnt lgkmcnt(8)
	v_mfma_f32_32x32x16_bf16 v[80:95], v[32:35], v[208:211], v[80:95]
	ds_read_b64 v[32:33], v236 offset:8192
	ds_read_b64 v[34:35], v237 offset:8192
	v_exp_f32_e32 v46, v46
	v_exp_f32_e32 v47, v47
	v_add_f32_e32 v0, v44, v0
	v_add_f32_e32 v0, v45, v0
	v_add_f32_e32 v0, v46, v0
	v_add_f32_e32 v0, v47, v0
	v_cvt_pk_bf16_f32 v2, v40, v41
	v_cvt_pk_bf16_f32 v3, v42, v43
	v_cvt_pk_bf16_f32 v4, v44, v45
	v_cvt_pk_bf16_f32 v5, v46, v47
	s_nop 1
	ds_read_b64 v[40:41], v238 offset:20480
	ds_read_b64 v[42:43], v239 offset:20480
	ds_read_b64 v[44:45], v238 offset:12288
	ds_read_b64 v[46:47], v239 offset:12288
	s_waitcnt lgkmcnt(12)
	v_mfma_f32_32x32x16_bf16 v[112:127], v[36:39], v[2:5], v[112:127]
	ds_read_b64 v[36:37], v238 offset:16384
	ds_read_b64 v[38:39], v239 offset:16384
	v_exp_f32_e32 v48, v48
	v_exp_f32_e32 v49, v49
	s_waitcnt lgkmcnt(12)
	v_mfma_f32_32x32x16_bf16 v[64:79], v[6:9], v[2:5], v[64:79]
	ds_read_b64 v[6:7], v240 offset:8192
	ds_read_b64 v[8:9], v241 offset:8192
	v_exp_f32_e32 v50, v50
	v_exp_f32_e32 v51, v51
	v_add_f32_e32 v0, v48, v0
	v_add_f32_e32 v0, v49, v0
	s_waitcnt lgkmcnt(12)
	v_mfma_f32_32x32x16_bf16 v[96:111], v[10:13], v[2:5], v[96:111]
	ds_read_b64 v[10:11], v242 offset:12288
	ds_read_b64 v[12:13], v243 offset:12288
	v_exp_f32_e32 v52, v52
	v_exp_f32_e32 v53, v53
	v_add_f32_e32 v0, v50, v0
	v_add_f32_e32 v0, v51, v0
	s_waitcnt lgkmcnt(12)
	v_mfma_f32_32x32x16_bf16 v[80:95], v[244:247], v[2:5], v[80:95]
	ds_read_b64 v[244:245], v242 offset:16384
	ds_read_b64 v[246:247], v243 offset:16384
	v_exp_f32_e32 v54, v54
	v_exp_f32_e32 v55, v55
	v_add_f32_e32 v0, v52, v0
	v_add_f32_e32 v0, v53, v0
	v_add_f32_e32 v0, v54, v0
	v_add_f32_e32 v0, v55, v0
	v_cvt_pk_bf16_f32 v2, v48, v49
	v_cvt_pk_bf16_f32 v3, v50, v51
	v_cvt_pk_bf16_f32 v4, v52, v53
	v_cvt_pk_bf16_f32 v5, v54, v55
	s_nop 1
	ds_read_b64 v[48:49], v242 offset:20480
	ds_read_b64 v[50:51], v243 offset:20480
	s_waitcnt lgkmcnt(14)
	v_mfma_f32_32x32x16_bf16 v[112:127], v[32:35], v[2:5], v[112:127]
	v_exp_f32_e32 v56, v56
	v_exp_f32_e32 v57, v57
	s_waitcnt lgkmcnt(12)
	v_mfma_f32_32x32x16_bf16 v[64:79], v[40:43], v[2:5], v[64:79]
	v_exp_f32_e32 v58, v58
	v_exp_f32_e32 v59, v59
	v_add_f32_e32 v0, v56, v0
	v_add_f32_e32 v0, v57, v0
	s_waitcnt vmcnt(0) lgkmcnt(0)
	s_mov_b64 s[24:25], exec
	s_mov_b64 exec, 1
	v_mov_b32_e32 v248, s33
	v_mov_b32_e32 v249, 1
	ds_add_u32 v248, v249 offset:8
	s_mov_b64 exec, s[24:25]
	s_setprio 0
	s_waitcnt lgkmcnt(10)
	v_mfma_f32_32x32x16_bf16 v[96:111], v[44:47], v[2:5], v[96:111]
	v_exp_f32_e32 v60, v60
	v_exp_f32_e32 v61, v61
	v_add_f32_e32 v0, v58, v0
	v_add_f32_e32 v0, v59, v0
	s_waitcnt lgkmcnt(8)
	v_mfma_f32_32x32x16_bf16 v[80:95], v[36:39], v[2:5], v[80:95]
	v_exp_f32_e32 v62, v62
	v_exp_f32_e32 v63, v63
	v_add_f32_e32 v0, v60, v0
	v_add_f32_e32 v0, v61, v0
	v_add_f32_e32 v0, v62, v0
	v_add_f32_e32 v0, v63, v0
	v_cvt_pk_bf16_f32 v2, v56, v57
	v_cvt_pk_bf16_f32 v3, v58, v59
	v_cvt_pk_bf16_f32 v4, v60, v61
	v_cvt_pk_bf16_f32 v5, v62, v63
	s_nop 1
	s_waitcnt lgkmcnt(6)
	v_mfma_f32_32x32x16_bf16 v[112:127], v[6:9], v[2:5], v[112:127]
	s_waitcnt lgkmcnt(4)
	v_mfma_f32_32x32x16_bf16 v[96:111], v[10:13], v[2:5], v[96:111]
	s_waitcnt lgkmcnt(2)
	v_mfma_f32_32x32x16_bf16 v[80:95], v[244:247], v[2:5], v[80:95]
	s_waitcnt lgkmcnt(0)
	v_mfma_f32_32x32x16_bf16 v[64:79], v[48:51], v[2:5], v[64:79]
	v_add_f32_e32 v227, v227, v0
	s_branch .LBB0_1376

.LBB0_1381:
	s_setprio 1
	ds_read_b128 v[2:5], v222
	ds_read_b128 v[6:9], v222 offset:4096
	ds_read_b128 v[10:13], v223
	ds_read_b128 v[244:247], v223 offset:4096
	s_waitcnt lgkmcnt(3)
	v_mfma_f32_32x32x16_bf16 v[32:47], v[2:5], v[160:163], v[16:31]
	v_exp_f32_e32 v128, v128
	v_exp_f32_e32 v129, v129
	ds_read_b128 v[2:5], v224
	s_waitcnt lgkmcnt(3)
	v_mfma_f32_32x32x16_bf16 v[48:63], v[6:9], v[160:163], v[16:31]
	v_exp_f32_e32 v130, v130
	v_exp_f32_e32 v131, v131
	ds_read_b128 v[6:9], v224 offset:4096
	s_waitcnt lgkmcnt(3)
	v_mfma_f32_32x32x16_bf16 v[32:47], v[10:13], v[164:167], v[32:47]
	v_exp_f32_e32 v132, v132
	v_exp_f32_e32 v133, v133
	v_add_f32_e32 v0, 0, v128
	ds_read_b128 v[10:13], v225
	s_waitcnt lgkmcnt(3)
	v_mfma_f32_32x32x16_bf16 v[48:63], v[244:247], v[164:167], v[48:63]
	v_exp_f32_e32 v134, v134
	v_exp_f32_e32 v135, v135
	v_add_f32_e32 v0, v129, v0
	ds_read_b128 v[244:247], v225 offset:4096
	s_waitcnt lgkmcnt(3)
	v_mfma_f32_32x32x16_bf16 v[32:47], v[2:5], v[168:171], v[32:47]
	v_cvt_pk_bf16_f32 v208, v128, v129
	v_add_f32_e32 v0, v130, v0
	v_add_f32_e32 v0, v131, v0
	s_waitcnt lgkmcnt(2)
	v_mfma_f32_32x32x16_bf16 v[48:63], v[6:9], v[168:171], v[48:63]
	v_cvt_pk_bf16_f32 v209, v130, v131
	v_add_f32_e32 v0, v132, v0
	v_add_f32_e32 v0, v133, v0
	s_waitcnt lgkmcnt(1)
	v_mfma_f32_32x32x16_bf16 v[32:47], v[10:13], v[172:175], v[32:47]
	v_cvt_pk_bf16_f32 v210, v132, v133
	v_add_f32_e32 v0, v134, v0
	s_waitcnt lgkmcnt(0)
	v_mfma_f32_32x32x16_bf16 v[48:63], v[244:247], v[172:175], v[48:63]
	v_cvt_pk_bf16_f32 v211, v134, v135
	v_add_f32_e32 v0, v135, v0
	s_or_b64 exec, exec, s[20:21]
	s_and_saveexec_b64 s[20:21], s[4:5]
	ds_read_b64 v[6:7], v228 offset:32768
	ds_read_b64 v[8:9], v229 offset:32768
	ds_read_b64 v[10:11], v230 offset:45056
	ds_read_b64 v[12:13], v231 offset:45056
	ds_read_b64 v[244:245], v230 offset:36864
	ds_read_b64 v[246:247], v231 offset:36864
	ds_read_b64 v[128:129], v230 offset:40960
	ds_read_b64 v[130:131], v231 offset:40960
	ds_read_b64 v[132:133], v232 offset:32768
	ds_read_b64 v[134:135], v233 offset:32768
	s_waitcnt lgkmcnt(8)
	v_mfma_f32_32x32x16_bf16 v[112:127], v[6:9], v[208:211], v[112:127]
	ds_read_b64 v[6:7], v234 offset:45056
	ds_read_b64 v[8:9], v235 offset:45056
	v_exp_f32_e32 v136, v136
	v_exp_f32_e32 v137, v137
	s_waitcnt lgkmcnt(8)
	v_mfma_f32_32x32x16_bf16 v[64:79], v[10:13], v[208:211], v[64:79]
	ds_read_b64 v[10:11], v234 offset:36864
	ds_read_b64 v[12:13], v235 offset:36864
	v_exp_f32_e32 v138, v138
	v_exp_f32_e32 v139, v139
	v_add_f32_e32 v0, v136, v0
	v_add_f32_e32 v0, v137, v0
	s_waitcnt lgkmcnt(8)
	v_mfma_f32_32x32x16_bf16 v[96:111], v[244:247], v[208:211], v[96:111]
	ds_read_b64 v[244:245], v234 offset:40960
	ds_read_b64 v[246:247], v235 offset:40960
	v_exp_f32_e32 v140, v140
	v_exp_f32_e32 v141, v141
	v_add_f32_e32 v0, v138, v0
	v_add_f32_e32 v0, v139, v0
	s_waitcnt lgkmcnt(8)
	v_mfma_f32_32x32x16_bf16 v[80:95], v[128:131], v[208:211], v[80:95]
	ds_read_b64 v[128:129], v236 offset:32768
	ds_read_b64 v[130:131], v237 offset:32768
	v_exp_f32_e32 v142, v142
	v_exp_f32_e32 v143, v143
	v_add_f32_e32 v0, v140, v0
	v_add_f32_e32 v0, v141, v0
	v_add_f32_e32 v0, v142, v0
	v_add_f32_e32 v0, v143, v0
	v_cvt_pk_bf16_f32 v2, v136, v137
	v_cvt_pk_bf16_f32 v3, v138, v139
	v_cvt_pk_bf16_f32 v4, v140, v141
	v_cvt_pk_bf16_f32 v5, v142, v143
	s_nop 1
	ds_read_b64 v[136:137], v238 offset:45056
	ds_read_b64 v[138:139], v239 offset:45056
	ds_read_b64 v[140:141], v238 offset:36864
	ds_read_b64 v[142:143], v239 offset:36864
	s_waitcnt lgkmcnt(12)
	v_mfma_f32_32x32x16_bf16 v[112:127], v[132:135], v[2:5], v[112:127]
	ds_read_b64 v[132:133], v238 offset:40960
	ds_read_b64 v[134:135], v239 offset:40960
	v_exp_f32_e32 v144, v144
	v_exp_f32_e32 v145, v145
	s_waitcnt lgkmcnt(12)
	v_mfma_f32_32x32x16_bf16 v[64:79], v[6:9], v[2:5], v[64:79]
	ds_read_b64 v[6:7], v240 offset:32768
	ds_read_b64 v[8:9], v241 offset:32768
	v_exp_f32_e32 v146, v146
	v_exp_f32_e32 v147, v147
	v_add_f32_e32 v0, v144, v0
	v_add_f32_e32 v0, v145, v0
	s_waitcnt lgkmcnt(12)
	v_mfma_f32_32x32x16_bf16 v[96:111], v[10:13], v[2:5], v[96:111]
	ds_read_b64 v[10:11], v242 offset:36864
	ds_read_b64 v[12:13], v243 offset:36864
	v_exp_f32_e32 v148, v148
	v_exp_f32_e32 v149, v149
	v_add_f32_e32 v0, v146, v0
	v_add_f32_e32 v0, v147, v0
	s_waitcnt lgkmcnt(12)
	v_mfma_f32_32x32x16_bf16 v[80:95], v[244:247], v[2:5], v[80:95]
	ds_read_b64 v[244:245], v242 offset:40960
	ds_read_b64 v[246:247], v243 offset:40960
	v_exp_f32_e32 v150, v150
	v_exp_f32_e32 v151, v151
	v_add_f32_e32 v0, v148, v0
	v_add_f32_e32 v0, v149, v0
	v_add_f32_e32 v0, v150, v0
	v_add_f32_e32 v0, v151, v0
	v_cvt_pk_bf16_f32 v2, v144, v145
	v_cvt_pk_bf16_f32 v3, v146, v147
	v_cvt_pk_bf16_f32 v4, v148, v149
	v_cvt_pk_bf16_f32 v5, v150, v151
	s_nop 1
	ds_read_b64 v[144:145], v242 offset:45056
	ds_read_b64 v[146:147], v243 offset:45056
	s_waitcnt lgkmcnt(14)
	v_mfma_f32_32x32x16_bf16 v[112:127], v[128:131], v[2:5], v[112:127]
	v_exp_f32_e32 v152, v152
	v_exp_f32_e32 v153, v153
	s_waitcnt lgkmcnt(12)
	v_mfma_f32_32x32x16_bf16 v[64:79], v[136:139], v[2:5], v[64:79]
	v_exp_f32_e32 v154, v154
	v_exp_f32_e32 v155, v155
	v_add_f32_e32 v0, v152, v0
	v_add_f32_e32 v0, v153, v0
	s_waitcnt vmcnt(0) lgkmcnt(0)
	s_mov_b64 s[24:25], exec
	s_mov_b64 exec, 1
	v_mov_b32_e32 v248, s33
	v_mov_b32_e32 v249, 1
	ds_add_u32 v248, v249 offset:8
	s_mov_b64 exec, s[24:25]
	s_setprio 0
	s_waitcnt lgkmcnt(10)
	v_mfma_f32_32x32x16_bf16 v[96:111], v[140:143], v[2:5], v[96:111]
	v_exp_f32_e32 v156, v156
	v_exp_f32_e32 v157, v157
	v_add_f32_e32 v0, v154, v0
	v_add_f32_e32 v0, v155, v0
	s_waitcnt lgkmcnt(8)
	v_mfma_f32_32x32x16_bf16 v[80:95], v[132:135], v[2:5], v[80:95]
	v_exp_f32_e32 v158, v158
	v_exp_f32_e32 v159, v159
	v_add_f32_e32 v0, v156, v0
	v_add_f32_e32 v0, v157, v0
	v_add_f32_e32 v0, v158, v0
	v_add_f32_e32 v0, v159, v0
	v_cvt_pk_bf16_f32 v2, v152, v153
	v_cvt_pk_bf16_f32 v3, v154, v155
	v_cvt_pk_bf16_f32 v4, v156, v157
	v_cvt_pk_bf16_f32 v5, v158, v159
	s_nop 1
	s_waitcnt lgkmcnt(6)
	v_mfma_f32_32x32x16_bf16 v[112:127], v[6:9], v[2:5], v[112:127]
	s_waitcnt lgkmcnt(4)
	v_mfma_f32_32x32x16_bf16 v[96:111], v[10:13], v[2:5], v[96:111]
	s_waitcnt lgkmcnt(2)
	v_mfma_f32_32x32x16_bf16 v[80:95], v[244:247], v[2:5], v[80:95]
	s_waitcnt lgkmcnt(0)
	v_mfma_f32_32x32x16_bf16 v[64:79], v[144:147], v[2:5], v[64:79]
	v_add_f32_e32 v227, v0, v227
	s_or_b64 exec, exec, s[20:21]
	s_branch .LBB0_1389

.LBB0_1411:
	s_or_b32 s82, s31, 1
	s_lshl_b64 s[4:5], s[82:83], 7
	s_add_u32 s4, s8, s4
	s_addc_u32 s5, s9, s5
	s_add_u32 m0, s38, 0x8000
	s_nop 0
	global_load_lds_dwordx4 v196, s[4:5]
	s_add_u32 m0, s38, 0x9000
	s_nop 0
	global_load_lds_dwordx4 v197, s[4:5]
	s_add_u32 m0, s38, 0xa000
	s_nop 0
	global_load_lds_dwordx4 v198, s[4:5]
	s_add_u32 m0, s38, 0xb000
	s_nop 0
	global_load_lds_dwordx4 v199, s[4:5]
	v_cmp_lt_i32_e64 s[4:5], s31, v225
	s_and_saveexec_b64 s[22:23], s[4:5]
	s_cbranch_execz .LBB0_1413
	s_setprio 1
	ds_read_b128 v[2:5], v220 offset:24576
	ds_read_b128 v[6:9], v220 offset:28672
	ds_read_b128 v[10:13], v221 offset:24576
	ds_read_b128 v[244:247], v221 offset:28672
	s_waitcnt lgkmcnt(3)
	v_mfma_f32_32x32x16_bf16 v[128:143], v[2:5], v[160:163], v[16:31]
	v_exp_f32_e32 v80, v80
	v_exp_f32_e32 v81, v81
	ds_read_b128 v[2:5], v222 offset:24576
	s_waitcnt lgkmcnt(3)
	v_mfma_f32_32x32x16_bf16 v[144:159], v[6:9], v[160:163], v[16:31]
	v_exp_f32_e32 v82, v82
	v_exp_f32_e32 v83, v83
	ds_read_b128 v[6:9], v222 offset:28672
	s_waitcnt lgkmcnt(3)
	v_mfma_f32_32x32x16_bf16 v[128:143], v[10:13], v[164:167], v[128:143]
	v_exp_f32_e32 v84, v84
	v_exp_f32_e32 v85, v85
	v_add_f32_e32 v0, 0, v80
	ds_read_b128 v[10:13], v223 offset:24576
	s_waitcnt lgkmcnt(3)
	v_mfma_f32_32x32x16_bf16 v[144:159], v[244:247], v[164:167], v[144:159]
	v_exp_f32_e32 v86, v86
	v_exp_f32_e32 v87, v87
	v_add_f32_e32 v0, v81, v0
	ds_read_b128 v[244:247], v223 offset:28672
	s_waitcnt lgkmcnt(3)
	v_mfma_f32_32x32x16_bf16 v[128:143], v[2:5], v[168:171], v[128:143]
	v_cvt_pk_bf16_f32 v208, v80, v81
	v_add_f32_e32 v0, v82, v0
	v_add_f32_e32 v0, v83, v0
	s_waitcnt lgkmcnt(2)
	v_mfma_f32_32x32x16_bf16 v[144:159], v[6:9], v[168:171], v[144:159]
	v_cvt_pk_bf16_f32 v209, v82, v83
	v_add_f32_e32 v0, v84, v0
	v_add_f32_e32 v0, v85, v0
	s_waitcnt lgkmcnt(1)
	v_mfma_f32_32x32x16_bf16 v[128:143], v[10:13], v[172:175], v[128:143]
	v_cvt_pk_bf16_f32 v210, v84, v85
	v_add_f32_e32 v0, v86, v0
	s_waitcnt lgkmcnt(0)
	v_mfma_f32_32x32x16_bf16 v[144:159], v[244:247], v[172:175], v[144:159]
	v_cvt_pk_bf16_f32 v211, v86, v87
	v_add_f32_e32 v0, v87, v0
	s_or_b64 exec, exec, s[22:23]
	v_cmp_le_i32_e32 vcc, s31, v225
	s_and_saveexec_b64 s[22:23], vcc
	ds_read_b64 v[6:7], v226 offset:8192
	ds_read_b64 v[8:9], v227 offset:8192
	ds_read_b64 v[10:11], v228 offset:20480
	ds_read_b64 v[12:13], v229 offset:20480
	ds_read_b64 v[242:243], v228 offset:12288
	ds_read_b64 v[244:245], v229 offset:12288
	ds_read_b64 v[80:81], v228 offset:16384
	ds_read_b64 v[82:83], v229 offset:16384
	ds_read_b64 v[84:85], v230 offset:8192
	ds_read_b64 v[86:87], v231 offset:8192
	s_waitcnt lgkmcnt(8)
	v_mfma_f32_32x32x16_bf16 v[64:79], v[6:9], v[208:211], v[64:79]
	ds_read_b64 v[6:7], v232 offset:20480
	ds_read_b64 v[8:9], v233 offset:20480
	v_exp_f32_e32 v88, v88
	v_exp_f32_e32 v89, v89
	s_waitcnt lgkmcnt(8)
	v_mfma_f32_32x32x16_bf16 v[112:127], v[10:13], v[208:211], v[112:127]
	ds_read_b64 v[10:11], v232 offset:12288
	ds_read_b64 v[12:13], v233 offset:12288
	v_exp_f32_e32 v90, v90
	v_exp_f32_e32 v91, v91
	v_add_f32_e32 v0, v88, v0
	v_add_f32_e32 v0, v89, v0
	s_waitcnt lgkmcnt(8)
	v_mfma_f32_32x32x16_bf16 v[48:63], v[242:245], v[208:211], v[48:63]
	ds_read_b64 v[242:243], v232 offset:16384
	ds_read_b64 v[244:245], v233 offset:16384
	v_exp_f32_e32 v92, v92
	v_exp_f32_e32 v93, v93
	v_add_f32_e32 v0, v90, v0
	v_add_f32_e32 v0, v91, v0
	s_waitcnt lgkmcnt(8)
	v_mfma_f32_32x32x16_bf16 v[32:47], v[80:83], v[208:211], v[32:47]
	ds_read_b64 v[80:81], v234 offset:8192
	ds_read_b64 v[82:83], v235 offset:8192
	v_exp_f32_e32 v94, v94
	v_exp_f32_e32 v95, v95
	v_add_f32_e32 v0, v92, v0
	v_add_f32_e32 v0, v93, v0
	v_add_f32_e32 v0, v94, v0
	v_add_f32_e32 v0, v95, v0
	v_cvt_pk_bf16_f32 v2, v88, v89
	v_cvt_pk_bf16_f32 v3, v90, v91
	v_cvt_pk_bf16_f32 v4, v92, v93
	v_cvt_pk_bf16_f32 v5, v94, v95
	s_nop 1
	ds_read_b64 v[88:89], v236 offset:20480
	ds_read_b64 v[90:91], v237 offset:20480
	ds_read_b64 v[92:93], v236 offset:12288
	ds_read_b64 v[94:95], v237 offset:12288
	s_waitcnt lgkmcnt(12)
	v_mfma_f32_32x32x16_bf16 v[64:79], v[84:87], v[2:5], v[64:79]
	ds_read_b64 v[84:85], v236 offset:16384
	ds_read_b64 v[86:87], v237 offset:16384
	v_exp_f32_e32 v96, v96
	v_exp_f32_e32 v97, v97
	s_waitcnt lgkmcnt(12)
	v_mfma_f32_32x32x16_bf16 v[112:127], v[6:9], v[2:5], v[112:127]
	ds_read_b64 v[6:7], v238 offset:8192
	ds_read_b64 v[8:9], v239 offset:8192
	v_exp_f32_e32 v98, v98
	v_exp_f32_e32 v99, v99
	v_add_f32_e32 v0, v96, v0
	v_add_f32_e32 v0, v97, v0
	s_waitcnt lgkmcnt(12)
	v_mfma_f32_32x32x16_bf16 v[48:63], v[10:13], v[2:5], v[48:63]
	ds_read_b64 v[10:11], v240 offset:12288
	ds_read_b64 v[12:13], v241 offset:12288
	v_exp_f32_e32 v100, v100
	v_exp_f32_e32 v101, v101
	v_add_f32_e32 v0, v98, v0
	v_add_f32_e32 v0, v99, v0
	s_waitcnt lgkmcnt(12)
	v_mfma_f32_32x32x16_bf16 v[32:47], v[242:245], v[2:5], v[32:47]
	ds_read_b64 v[242:243], v240 offset:16384
	ds_read_b64 v[244:245], v241 offset:16384
	v_exp_f32_e32 v102, v102
	v_exp_f32_e32 v103, v103
	v_add_f32_e32 v0, v100, v0
	v_add_f32_e32 v0, v101, v0
	v_add_f32_e32 v0, v102, v0
	v_add_f32_e32 v0, v103, v0
	v_cvt_pk_bf16_f32 v2, v96, v97
	v_cvt_pk_bf16_f32 v3, v98, v99
	v_cvt_pk_bf16_f32 v4, v100, v101
	v_cvt_pk_bf16_f32 v5, v102, v103
	s_nop 1
	ds_read_b64 v[96:97], v240 offset:20480
	ds_read_b64 v[98:99], v241 offset:20480
	s_waitcnt lgkmcnt(14)
	v_mfma_f32_32x32x16_bf16 v[64:79], v[80:83], v[2:5], v[64:79]
	v_exp_f32_e32 v104, v104
	v_exp_f32_e32 v105, v105
	s_waitcnt lgkmcnt(12)
	v_mfma_f32_32x32x16_bf16 v[112:127], v[88:91], v[2:5], v[112:127]
	v_exp_f32_e32 v106, v106
	v_exp_f32_e32 v107, v107
	v_add_f32_e32 v0, v104, v0
	v_add_f32_e32 v0, v105, v0
	s_waitcnt vmcnt(0) lgkmcnt(0)
	s_mov_b64 s[24:25], exec
	s_mov_b64 exec, 1
	v_mov_b32_e32 v248, s33
	v_mov_b32_e32 v249, 1
	ds_add_u32 v248, v249 offset:8
	s_mov_b64 exec, s[24:25]
	s_setprio 0
	s_waitcnt lgkmcnt(10)
	v_mfma_f32_32x32x16_bf16 v[48:63], v[92:95], v[2:5], v[48:63]
	v_exp_f32_e32 v108, v108
	v_exp_f32_e32 v109, v109
	v_add_f32_e32 v0, v106, v0
	v_add_f32_e32 v0, v107, v0
	s_waitcnt lgkmcnt(8)
	v_mfma_f32_32x32x16_bf16 v[32:47], v[84:87], v[2:5], v[32:47]
	v_exp_f32_e32 v110, v110
	v_exp_f32_e32 v111, v111
	v_add_f32_e32 v0, v108, v0
	v_add_f32_e32 v0, v109, v0
	v_add_f32_e32 v0, v110, v0
	v_add_f32_e32 v0, v111, v0
	v_cvt_pk_bf16_f32 v2, v104, v105
	v_cvt_pk_bf16_f32 v3, v106, v107
	v_cvt_pk_bf16_f32 v4, v108, v109
	v_cvt_pk_bf16_f32 v5, v110, v111
	s_nop 1
	s_waitcnt lgkmcnt(6)
	v_mfma_f32_32x32x16_bf16 v[64:79], v[6:9], v[2:5], v[64:79]
	s_waitcnt lgkmcnt(4)
	v_mfma_f32_32x32x16_bf16 v[48:63], v[10:13], v[2:5], v[48:63]
	s_waitcnt lgkmcnt(2)
	v_mfma_f32_32x32x16_bf16 v[32:47], v[242:245], v[2:5], v[32:47]
	s_waitcnt lgkmcnt(0)
	v_mfma_f32_32x32x16_bf16 v[112:127], v[96:99], v[2:5], v[112:127]
	v_add_f32_e32 v224, v224, v0
	s_branch .LBB0_1418

.LBB0_1423:
	s_setprio 1
	ds_read_b128 v[2:5], v220
	ds_read_b128 v[6:9], v220 offset:4096
	ds_read_b128 v[10:13], v221
	ds_read_b128 v[244:247], v221 offset:4096
	s_waitcnt lgkmcnt(3)
	v_mfma_f32_32x32x16_bf16 v[80:95], v[2:5], v[160:163], v[16:31]
	v_exp_f32_e32 v128, v128
	v_exp_f32_e32 v129, v129
	ds_read_b128 v[2:5], v222
	s_waitcnt lgkmcnt(3)
	v_mfma_f32_32x32x16_bf16 v[96:111], v[6:9], v[160:163], v[16:31]
	v_exp_f32_e32 v130, v130
	v_exp_f32_e32 v131, v131
	ds_read_b128 v[6:9], v222 offset:4096
	s_waitcnt lgkmcnt(3)
	v_mfma_f32_32x32x16_bf16 v[80:95], v[10:13], v[164:167], v[80:95]
	v_exp_f32_e32 v132, v132
	v_exp_f32_e32 v133, v133
	v_add_f32_e32 v0, 0, v128
	ds_read_b128 v[10:13], v223
	s_waitcnt lgkmcnt(3)
	v_mfma_f32_32x32x16_bf16 v[96:111], v[244:247], v[164:167], v[96:111]
	v_exp_f32_e32 v134, v134
	v_exp_f32_e32 v135, v135
	v_add_f32_e32 v0, v129, v0
	ds_read_b128 v[244:247], v223 offset:4096
	s_waitcnt lgkmcnt(3)
	v_mfma_f32_32x32x16_bf16 v[80:95], v[2:5], v[168:171], v[80:95]
	v_cvt_pk_bf16_f32 v208, v128, v129
	v_add_f32_e32 v0, v130, v0
	v_add_f32_e32 v0, v131, v0
	s_waitcnt lgkmcnt(2)
	v_mfma_f32_32x32x16_bf16 v[96:111], v[6:9], v[168:171], v[96:111]
	v_cvt_pk_bf16_f32 v209, v130, v131
	v_add_f32_e32 v0, v132, v0
	v_add_f32_e32 v0, v133, v0
	s_waitcnt lgkmcnt(1)
	v_mfma_f32_32x32x16_bf16 v[80:95], v[10:13], v[172:175], v[80:95]
	v_cvt_pk_bf16_f32 v210, v132, v133
	v_add_f32_e32 v0, v134, v0
	s_waitcnt lgkmcnt(0)
	v_mfma_f32_32x32x16_bf16 v[96:111], v[244:247], v[172:175], v[96:111]
	v_cvt_pk_bf16_f32 v211, v134, v135
	v_add_f32_e32 v0, v135, v0
	s_or_b64 exec, exec, s[20:21]
	s_and_saveexec_b64 s[20:21], s[4:5]
	ds_read_b64 v[6:7], v226 offset:32768
	ds_read_b64 v[8:9], v227 offset:32768
	ds_read_b64 v[10:11], v228 offset:45056
	ds_read_b64 v[12:13], v229 offset:45056
	ds_read_b64 v[242:243], v228 offset:36864
	ds_read_b64 v[244:245], v229 offset:36864
	ds_read_b64 v[128:129], v228 offset:40960
	ds_read_b64 v[130:131], v229 offset:40960
	ds_read_b64 v[132:133], v230 offset:32768
	ds_read_b64 v[134:135], v231 offset:32768
	s_waitcnt lgkmcnt(8)
	v_mfma_f32_32x32x16_bf16 v[64:79], v[6:9], v[208:211], v[64:79]
	ds_read_b64 v[6:7], v232 offset:45056
	ds_read_b64 v[8:9], v233 offset:45056
	v_exp_f32_e32 v136, v136
	v_exp_f32_e32 v137, v137
	s_waitcnt lgkmcnt(8)
	v_mfma_f32_32x32x16_bf16 v[112:127], v[10:13], v[208:211], v[112:127]
	ds_read_b64 v[10:11], v232 offset:36864
	ds_read_b64 v[12:13], v233 offset:36864
	v_exp_f32_e32 v138, v138
	v_exp_f32_e32 v139, v139
	v_add_f32_e32 v0, v136, v0
	v_add_f32_e32 v0, v137, v0
	s_waitcnt lgkmcnt(8)
	v_mfma_f32_32x32x16_bf16 v[48:63], v[242:245], v[208:211], v[48:63]
	ds_read_b64 v[242:243], v232 offset:40960
	ds_read_b64 v[244:245], v233 offset:40960
	v_exp_f32_e32 v140, v140
	v_exp_f32_e32 v141, v141
	v_add_f32_e32 v0, v138, v0
	v_add_f32_e32 v0, v139, v0
	s_waitcnt lgkmcnt(8)
	v_mfma_f32_32x32x16_bf16 v[32:47], v[128:131], v[208:211], v[32:47]
	ds_read_b64 v[128:129], v234 offset:32768
	ds_read_b64 v[130:131], v235 offset:32768
	v_exp_f32_e32 v142, v142
	v_exp_f32_e32 v143, v143
	v_add_f32_e32 v0, v140, v0
	v_add_f32_e32 v0, v141, v0
	v_add_f32_e32 v0, v142, v0
	v_add_f32_e32 v0, v143, v0
	v_cvt_pk_bf16_f32 v2, v136, v137
	v_cvt_pk_bf16_f32 v3, v138, v139
	v_cvt_pk_bf16_f32 v4, v140, v141
	v_cvt_pk_bf16_f32 v5, v142, v143
	s_nop 1
	ds_read_b64 v[136:137], v236 offset:45056
	ds_read_b64 v[138:139], v237 offset:45056
	ds_read_b64 v[140:141], v236 offset:36864
	ds_read_b64 v[142:143], v237 offset:36864
	s_waitcnt lgkmcnt(12)
	v_mfma_f32_32x32x16_bf16 v[64:79], v[132:135], v[2:5], v[64:79]
	ds_read_b64 v[132:133], v236 offset:40960
	ds_read_b64 v[134:135], v237 offset:40960
	v_exp_f32_e32 v144, v144
	v_exp_f32_e32 v145, v145
	s_waitcnt lgkmcnt(12)
	v_mfma_f32_32x32x16_bf16 v[112:127], v[6:9], v[2:5], v[112:127]
	ds_read_b64 v[6:7], v238 offset:32768
	ds_read_b64 v[8:9], v239 offset:32768
	v_exp_f32_e32 v146, v146
	v_exp_f32_e32 v147, v147
	v_add_f32_e32 v0, v144, v0
	v_add_f32_e32 v0, v145, v0
	s_waitcnt lgkmcnt(12)
	v_mfma_f32_32x32x16_bf16 v[48:63], v[10:13], v[2:5], v[48:63]
	ds_read_b64 v[10:11], v240 offset:36864
	ds_read_b64 v[12:13], v241 offset:36864
	v_exp_f32_e32 v148, v148
	v_exp_f32_e32 v149, v149
	v_add_f32_e32 v0, v146, v0
	v_add_f32_e32 v0, v147, v0
	s_waitcnt lgkmcnt(12)
	v_mfma_f32_32x32x16_bf16 v[32:47], v[242:245], v[2:5], v[32:47]
	ds_read_b64 v[242:243], v240 offset:40960
	ds_read_b64 v[244:245], v241 offset:40960
	v_exp_f32_e32 v150, v150
	v_exp_f32_e32 v151, v151
	v_add_f32_e32 v0, v148, v0
	v_add_f32_e32 v0, v149, v0
	v_add_f32_e32 v0, v150, v0
	v_add_f32_e32 v0, v151, v0
	v_cvt_pk_bf16_f32 v2, v144, v145
	v_cvt_pk_bf16_f32 v3, v146, v147
	v_cvt_pk_bf16_f32 v4, v148, v149
	v_cvt_pk_bf16_f32 v5, v150, v151
	s_nop 1
	ds_read_b64 v[144:145], v240 offset:45056
	ds_read_b64 v[146:147], v241 offset:45056
	s_waitcnt lgkmcnt(14)
	v_mfma_f32_32x32x16_bf16 v[64:79], v[128:131], v[2:5], v[64:79]
	v_exp_f32_e32 v152, v152
	v_exp_f32_e32 v153, v153
	s_waitcnt lgkmcnt(12)
	v_mfma_f32_32x32x16_bf16 v[112:127], v[136:139], v[2:5], v[112:127]
	v_exp_f32_e32 v154, v154
	v_exp_f32_e32 v155, v155
	v_add_f32_e32 v0, v152, v0
	v_add_f32_e32 v0, v153, v0
	s_waitcnt vmcnt(0) lgkmcnt(0)
	s_mov_b64 s[24:25], exec
	s_mov_b64 exec, 1
	v_mov_b32_e32 v248, s33
	v_mov_b32_e32 v249, 1
	ds_add_u32 v248, v249 offset:8
	s_mov_b64 exec, s[24:25]
	s_setprio 0
	s_waitcnt lgkmcnt(10)
	v_mfma_f32_32x32x16_bf16 v[48:63], v[140:143], v[2:5], v[48:63]
	v_exp_f32_e32 v156, v156
	v_exp_f32_e32 v157, v157
	v_add_f32_e32 v0, v154, v0
	v_add_f32_e32 v0, v155, v0
	s_waitcnt lgkmcnt(8)
	v_mfma_f32_32x32x16_bf16 v[32:47], v[132:135], v[2:5], v[32:47]
	v_exp_f32_e32 v158, v158
	v_exp_f32_e32 v159, v159
	v_add_f32_e32 v0, v156, v0
	v_add_f32_e32 v0, v157, v0
	v_add_f32_e32 v0, v158, v0
	v_add_f32_e32 v0, v159, v0
	v_cvt_pk_bf16_f32 v2, v152, v153
	v_cvt_pk_bf16_f32 v3, v154, v155
	v_cvt_pk_bf16_f32 v4, v156, v157
	v_cvt_pk_bf16_f32 v5, v158, v159
	s_nop 1
	s_waitcnt lgkmcnt(6)
	v_mfma_f32_32x32x16_bf16 v[64:79], v[6:9], v[2:5], v[64:79]
	s_waitcnt lgkmcnt(4)
	v_mfma_f32_32x32x16_bf16 v[48:63], v[10:13], v[2:5], v[48:63]
	s_waitcnt lgkmcnt(2)
	v_mfma_f32_32x32x16_bf16 v[32:47], v[242:245], v[2:5], v[32:47]
	s_waitcnt lgkmcnt(0)
	v_mfma_f32_32x32x16_bf16 v[112:127], v[144:147], v[2:5], v[112:127]
	v_add_f32_e32 v224, v0, v224
	s_or_b64 exec, exec, s[20:21]
	s_branch .LBB0_1431
